# v24: v23 + the cache items of the compression MLP (needed two phases later) moved out of their own phase into the prompt-attention phase, next to the memory-bound HGRN output items of the order split
# baseline (speedup 1.0000x reference)
.LBB0_1057:
	v_add_u32_e32 v2, s43, v6
	v_cndmask_b32_e64 v0, 0, 1, s[46:47]
	v_ashrrev_i32_e32 v3, 31, v2
	v_readlane_b32 s46, v238, 8
	v_cmp_ne_u32_e64 s[0:1], 1, v0
	v_lshlrev_b64 v[0:1], 2, v[2:3]
	v_readlane_b32 s47, v238, 9
	v_lshl_add_u64 v[2:3], v[2:3], 1, s[36:37]
	s_mov_b32 s43, 0x10000
	v_lshl_add_u64 v[4:5], s[46:47], 0, v[0:1]
	v_add_co_u32_e32 v8, vcc, 0x10000, v4
	global_load_dword v130, v[4:5], off
	global_load_dword v133, v7, s[6:7]
	v_addc_co_u32_e32 v9, vcc, 0, v5, vcc
	global_load_dword v128, v[8:9], off
	global_load_dword v132, v7, s[6:7] offset:512
	v_add_co_u32_e32 v8, vcc, 0x20000, v4
	v_readlane_b32 s46, v238, 10
	s_nop 0
	v_addc_co_u32_e32 v9, vcc, 0, v5, vcc
	global_load_dword v126, v[8:9], off
	global_load_dword v131, v7, s[6:7] offset:1024
	v_add_co_u32_e32 v8, vcc, 0x30000, v4
	v_readlane_b32 s47, v238, 11
	s_nop 0
	v_addc_co_u32_e32 v9, vcc, 0, v5, vcc
	global_load_dword v124, v[8:9], off
	global_load_dword v129, v7, s[6:7] offset:1536
	v_add_co_u32_e32 v8, vcc, 0x40000, v4
	v_lshl_add_u64 v[0:1], s[38:39], 0, v[0:1]
	s_nop 0
	v_addc_co_u32_e32 v9, vcc, 0, v5, vcc
	global_load_dword v122, v[8:9], off
	global_load_dword v127, v7, s[6:7] offset:2048
	v_add_co_u32_e32 v8, vcc, 0x50000, v4
	s_waitcnt vmcnt(0)
	v_fmac_f32_e32 v130, 0, v133
	v_addc_co_u32_e32 v9, vcc, 0, v5, vcc
	global_load_dword v120, v[8:9], off
	global_load_dword v125, v7, s[6:7] offset:2560
	v_add_co_u32_e32 v8, vcc, 0x60000, v4
	v_bfe_u32 v133, v130, 16, 1
	s_nop 0
	v_addc_co_u32_e32 v9, vcc, 0, v5, vcc
	global_load_dword v118, v[8:9], off
	global_load_dword v123, v7, s[6:7] offset:3072
	v_add_co_u32_e32 v8, vcc, 0x70000, v4
	v_fmac_f32_e32 v128, v130, v132
	s_nop 0
	v_addc_co_u32_e32 v9, vcc, 0, v5, vcc
	global_load_dword v116, v[8:9], off
	global_load_dword v121, v7, s[6:7] offset:3584
	v_add_co_u32_e32 v8, vcc, 0x80000, v4
	global_load_dword v119, v7, s[46:47]
	s_nop 0
	v_addc_co_u32_e32 v9, vcc, 0, v5, vcc
	global_load_dword v113, v[8:9], off
	v_add_co_u32_e32 v8, vcc, 0x90000, v4
	v_readlane_b32 s46, v238, 12
	s_nop 0
	v_addc_co_u32_e32 v9, vcc, 0, v5, vcc
	v_readlane_b32 s47, v238, 13
	global_load_dword v111, v[8:9], off
	v_add3_u32 v133, v130, v133, s42
	v_bfe_u32 v130, v128, 16, 1
	v_add3_u32 v130, v128, v130, s42
	v_fmac_f32_e32 v126, v128, v131
	global_load_dword v117, v7, s[46:47]
	v_add_co_u32_e32 v8, vcc, 0xa0000, v4
	v_readlane_b32 s46, v238, 14
	s_nop 0
	v_addc_co_u32_e32 v9, vcc, 0, v5, vcc
	v_readlane_b32 s47, v238, 15
	global_load_dword v109, v[8:9], off
	v_bfe_u32 v128, v126, 16, 1
	v_add3_u32 v128, v126, v128, s42
	v_fmac_f32_e32 v124, v126, v129
	v_bfe_u32 v126, v124, 16, 1
	global_load_dword v115, v7, s[46:47]
	v_add_co_u32_e32 v8, vcc, 0xb0000, v4
	v_readlane_b32 s46, v238, 16
	s_nop 0
	v_addc_co_u32_e32 v9, vcc, 0, v5, vcc
	v_readlane_b32 s47, v238, 17
	global_load_dword v107, v[8:9], off
	v_add3_u32 v126, v124, v126, s42
	v_fmac_f32_e32 v122, v124, v127
	v_bfe_u32 v124, v122, 16, 1
	v_add3_u32 v124, v122, v124, s42
	global_load_dword v114, v7, s[46:47]
	v_add_co_u32_e32 v8, vcc, 0xc0000, v4
	v_readlane_b32 s46, v238, 18
	s_nop 0
	v_addc_co_u32_e32 v9, vcc, 0, v5, vcc
	v_readlane_b32 s47, v238, 19
	global_load_dword v105, v[8:9], off
	s_waitcnt vmcnt(0)
	v_fmac_f32_e32 v120, v122, v125
	s_nop 1
	global_load_dword v112, v7, s[46:47]
	v_add_co_u32_e32 v8, vcc, 0xd0000, v4
	v_readlane_b32 s46, v238, 20
	s_nop 0
	v_addc_co_u32_e32 v9, vcc, 0, v5, vcc
	v_readlane_b32 s47, v238, 21
	global_load_dword v103, v[8:9], off
	v_bfe_u32 v122, v120, 16, 1
	v_add3_u32 v122, v120, v122, s42
	v_fmac_f32_e32 v118, v120, v123
	v_bfe_u32 v120, v118, 16, 1
	global_load_dword v110, v7, s[46:47]
	v_add_co_u32_e32 v8, vcc, 0xe0000, v4
	v_readlane_b32 s46, v238, 34
	s_nop 0
	v_addc_co_u32_e32 v9, vcc, 0, v5, vcc
	v_readlane_b32 s47, v238, 35
	global_load_dword v101, v[8:9], off
	v_add3_u32 v120, v118, v120, s42
	v_fmac_f32_e32 v116, v118, v121
	v_bfe_u32 v118, v116, 16, 1
	v_add3_u32 v118, v116, v118, s42
	global_load_dword v108, v7, s[46:47]
	v_add_co_u32_e32 v8, vcc, 0xf0000, v4
	v_readlane_b32 s46, v238, 22
	s_nop 0
	v_addc_co_u32_e32 v9, vcc, 0, v5, vcc
	v_readlane_b32 s47, v238, 23
	global_load_dword v99, v[8:9], off
	v_fmac_f32_e32 v113, v116, v119
	v_bfe_u32 v116, v113, 16, 1
	v_add3_u32 v116, v113, v116, s42
	v_fmac_f32_e32 v111, v113, v117
	global_load_dword v106, v7, s[46:47]
	v_add_co_u32_e32 v8, vcc, 0x100000, v4
	v_readlane_b32 s46, v238, 24
	s_nop 0
	v_addc_co_u32_e32 v9, vcc, 0, v5, vcc
	v_readlane_b32 s47, v238, 25
	global_load_dword v97, v[8:9], off
	v_bfe_u32 v113, v111, 16, 1
	v_add3_u32 v113, v111, v113, s42
	v_fmac_f32_e32 v109, v111, v115
	v_bfe_u32 v111, v109, 16, 1
	global_load_dword v104, v7, s[46:47]
	v_add_co_u32_e32 v8, vcc, 0x110000, v4
	v_readlane_b32 s46, v238, 26
	s_nop 0
	v_addc_co_u32_e32 v9, vcc, 0, v5, vcc
	v_readlane_b32 s47, v238, 27
	global_load_dword v95, v[8:9], off
	v_fmac_f32_e32 v107, v109, v114
	v_add3_u32 v111, v109, v111, s42
	v_bfe_u32 v109, v107, 16, 1
	v_add3_u32 v109, v107, v109, s42
	global_load_dword v102, v7, s[46:47]
	v_add_co_u32_e32 v8, vcc, 0x120000, v4
	v_readlane_b32 s46, v238, 28
	s_nop 0
	v_addc_co_u32_e32 v9, vcc, 0, v5, vcc
	v_readlane_b32 s47, v238, 29
	global_load_dword v93, v[8:9], off
	s_waitcnt vmcnt(0)
	v_fmac_f32_e32 v105, v107, v112
	s_nop 1
	global_load_dword v100, v7, s[46:47]
	v_add_co_u32_e32 v8, vcc, 0x130000, v4
	v_readlane_b32 s46, v238, 30
	s_nop 0
	v_addc_co_u32_e32 v9, vcc, 0, v5, vcc
	v_readlane_b32 s47, v238, 31
	global_load_dword v91, v[8:9], off
	v_bfe_u32 v107, v105, 16, 1
	v_add3_u32 v107, v105, v107, s42
	v_fmac_f32_e32 v103, v105, v110
	s_nop 0
	global_load_dword v98, v7, s[46:47]
	v_add_co_u32_e32 v8, vcc, 0x140000, v4
	v_readlane_b32 s46, v238, 32
	s_nop 0
	v_addc_co_u32_e32 v9, vcc, 0, v5, vcc
	v_readlane_b32 s47, v238, 33
	global_load_dword v89, v[8:9], off
	v_bfe_u32 v105, v103, 16, 1
	v_add3_u32 v105, v103, v105, s42
	v_fmac_f32_e32 v101, v103, v108
	s_nop 0
	global_load_dword v96, v7, s[46:47]
	v_add_co_u32_e32 v8, vcc, 0x150000, v4
	v_readlane_b32 s46, v238, 42
	s_nop 0
	v_addc_co_u32_e32 v9, vcc, 0, v5, vcc
	v_readlane_b32 s47, v238, 43
	global_load_dword v88, v[8:9], off
	v_bfe_u32 v103, v101, 16, 1
	v_add3_u32 v103, v101, v103, s42
	v_fmac_f32_e32 v99, v101, v106
	s_nop 0
	global_load_dword v94, v7, s[46:47]
	v_add_co_u32_e32 v8, vcc, 0x160000, v4
	v_readlane_b32 s46, v238, 44
	s_nop 0
	v_addc_co_u32_e32 v9, vcc, 0, v5, vcc
	v_readlane_b32 s47, v238, 45
	global_load_dword v86, v[8:9], off
	v_bfe_u32 v101, v99, 16, 1
	v_add3_u32 v101, v99, v101, s42
	v_fmac_f32_e32 v97, v99, v104
	s_nop 0
	global_load_dword v92, v7, s[46:47]
	v_add_co_u32_e32 v8, vcc, 0x170000, v4
	v_readlane_b32 s46, v238, 46
	s_nop 0
	v_addc_co_u32_e32 v9, vcc, 0, v5, vcc
	v_readlane_b32 s47, v238, 47
	global_load_dword v84, v[8:9], off
	v_bfe_u32 v99, v97, 16, 1
	v_add3_u32 v99, v97, v99, s42
	v_fmac_f32_e32 v95, v97, v102
	s_nop 0
	global_load_dword v90, v7, s[46:47]
	v_add_co_u32_e32 v8, vcc, 0x180000, v4
	v_bfe_u32 v97, v95, 16, 1
	s_nop 0
	v_addc_co_u32_e32 v9, vcc, 0, v5, vcc
	global_load_dword v82, v[8:9], off
	global_load_dword v87, v7, s[48:49]
	v_add_co_u32_e32 v8, vcc, 0x190000, v4
	v_add3_u32 v97, v95, v97, s42
	s_nop 0
	v_addc_co_u32_e32 v9, vcc, 0, v5, vcc
	global_load_dword v80, v[8:9], off
	global_load_dword v85, v7, s[50:51]
	v_add_co_u32_e32 v8, vcc, 0x1a0000, v4
	s_mov_b64 s[46:47], 0
	s_nop 0
	v_addc_co_u32_e32 v9, vcc, 0, v5, vcc
	global_load_dword v78, v[8:9], off
	global_load_dword v83, v7, s[54:55]
	v_add_co_u32_e32 v8, vcc, 0x1b0000, v4
	s_waitcnt vmcnt(0)
	v_fmac_f32_e32 v93, v95, v100
	v_addc_co_u32_e32 v9, vcc, 0, v5, vcc
	global_load_dword v76, v[8:9], off
	global_load_dword v81, v7, s[60:61]
	v_add_co_u32_e32 v8, vcc, 0x1c0000, v4
	v_bfe_u32 v95, v93, 16, 1
	s_nop 0
	v_addc_co_u32_e32 v9, vcc, 0, v5, vcc
	global_load_dword v74, v[8:9], off
	global_load_dword v79, v7, s[62:63]
	v_add_co_u32_e32 v8, vcc, 0x1d0000, v4
	v_fmac_f32_e32 v91, v93, v98
	s_nop 0
	v_addc_co_u32_e32 v9, vcc, 0, v5, vcc
	global_load_dword v72, v[8:9], off
	global_load_dword v77, v7, s[64:65]
	v_add_co_u32_e32 v8, vcc, 0x1e0000, v4
	v_add3_u32 v95, v93, v95, s42
	s_nop 0
	v_addc_co_u32_e32 v9, vcc, 0, v5, vcc
	global_load_dword v70, v[8:9], off
	global_load_dword v75, v7, s[70:71]
	v_add_co_u32_e32 v8, vcc, 0x1f0000, v4
	v_bfe_u32 v93, v91, 16, 1
	s_nop 0
	v_addc_co_u32_e32 v9, vcc, 0, v5, vcc
	global_load_dword v68, v[8:9], off
	global_load_dword v73, v7, s[78:79]
	v_add_co_u32_e32 v8, vcc, 0x200000, v4
	v_fmac_f32_e32 v89, v91, v96
	s_nop 0
	v_addc_co_u32_e32 v9, vcc, 0, v5, vcc
	global_load_dword v66, v[8:9], off
	global_load_dword v71, v7, s[80:81]
	v_add_co_u32_e32 v8, vcc, 0x210000, v4
	v_add3_u32 v93, v91, v93, s42
	s_nop 0
	v_addc_co_u32_e32 v9, vcc, 0, v5, vcc
	global_load_dword v64, v[8:9], off
	global_load_dword v69, v7, s[82:83]
	v_add_co_u32_e32 v8, vcc, 0x220000, v4
	v_bfe_u32 v91, v89, 16, 1
	s_nop 0
	v_addc_co_u32_e32 v9, vcc, 0, v5, vcc
	global_load_dword v62, v[8:9], off
	global_load_dword v67, v7, s[86:87]
	v_add_co_u32_e32 v8, vcc, 0x230000, v4
	v_fmac_f32_e32 v88, v89, v94
	s_nop 0
	v_addc_co_u32_e32 v9, vcc, 0, v5, vcc
	global_load_dword v60, v[8:9], off
	global_load_dword v65, v7, s[96:97]
	v_add_co_u32_e32 v8, vcc, 0x240000, v4
	v_add3_u32 v91, v89, v91, s42
	s_nop 0
	v_addc_co_u32_e32 v9, vcc, 0, v5, vcc
	global_load_dword v58, v[8:9], off
	global_load_dword v63, v7, s[8:9]
	v_add_co_u32_e32 v8, vcc, 0x250000, v4
	v_bfe_u32 v89, v88, 16, 1
	s_nop 0
	v_addc_co_u32_e32 v9, vcc, 0, v5, vcc
	global_load_dword v56, v[8:9], off
	global_load_dword v61, v7, s[94:95]
	v_add_co_u32_e32 v8, vcc, 0x260000, v4
	v_fmac_f32_e32 v86, v88, v92
	s_nop 0
	v_addc_co_u32_e32 v9, vcc, 0, v5, vcc
	global_load_dword v54, v[8:9], off
	global_load_dword v59, v7, s[40:41]
	v_add_co_u32_e32 v8, vcc, 0x270000, v4
	v_add3_u32 v89, v88, v89, s42
	s_nop 0
	v_addc_co_u32_e32 v9, vcc, 0, v5, vcc
	global_load_dword v52, v[8:9], off
	global_load_dword v57, v7, s[44:45]
	v_add_co_u32_e32 v8, vcc, 0x280000, v4
	v_bfe_u32 v88, v86, 16, 1
	s_nop 0
	v_addc_co_u32_e32 v9, vcc, 0, v5, vcc
	global_load_dword v50, v[8:9], off
	global_load_dword v55, v7, s[52:53]
	v_add_co_u32_e32 v8, vcc, 0x290000, v4
	v_fmac_f32_e32 v84, v86, v90
	s_nop 0
	v_addc_co_u32_e32 v9, vcc, 0, v5, vcc
	global_load_dword v48, v[8:9], off
	global_load_dword v53, v7, s[72:73]
	v_add_co_u32_e32 v8, vcc, 0x2a0000, v4
	v_fmac_f32_e32 v82, v84, v87
	s_nop 0
	v_addc_co_u32_e32 v9, vcc, 0, v5, vcc
	global_load_dword v46, v[8:9], off
	global_load_dword v51, v7, s[74:75]
	v_add_co_u32_e32 v8, vcc, 0x2b0000, v4
	v_fmac_f32_e32 v80, v82, v85
	s_nop 0
	v_addc_co_u32_e32 v9, vcc, 0, v5, vcc
	global_load_dword v44, v[8:9], off
	global_load_dword v49, v7, s[76:77]
	v_add_co_u32_e32 v8, vcc, 0x2c0000, v4
	v_fmac_f32_e32 v78, v80, v83
	s_nop 0
	v_addc_co_u32_e32 v9, vcc, 0, v5, vcc
	global_load_dword v42, v[8:9], off
	global_load_dword v47, v7, s[84:85]
	v_add_co_u32_e32 v8, vcc, 0x2d0000, v4
	s_waitcnt vmcnt(0)
	v_fmac_f32_e32 v76, v78, v81
	v_addc_co_u32_e32 v9, vcc, 0, v5, vcc
	global_load_dword v40, v[8:9], off
	global_load_dword v45, v7, s[92:93]
	v_add_co_u32_e32 v8, vcc, 0x2e0000, v4
	v_fmac_f32_e32 v74, v76, v79
	s_nop 0
	v_addc_co_u32_e32 v9, vcc, 0, v5, vcc
	global_load_dword v38, v[8:9], off
	global_load_dword v43, v7, s[2:3]
	v_add_co_u32_e32 v8, vcc, 0x2f0000, v4
	v_fmac_f32_e32 v72, v74, v77
	s_nop 0
	v_addc_co_u32_e32 v9, vcc, 0, v5, vcc
	global_load_dword v36, v[8:9], off
	global_load_dword v41, v7, s[56:57]
	v_add_co_u32_e32 v8, vcc, 0x300000, v4
	v_fmac_f32_e32 v70, v72, v75
	s_nop 0
	v_addc_co_u32_e32 v9, vcc, 0, v5, vcc
	global_load_dword v34, v[8:9], off
	global_load_dword v39, v7, s[58:59]
	v_add_co_u32_e32 v8, vcc, 0x310000, v4
	v_fmac_f32_e32 v68, v70, v73
	s_nop 0
	v_addc_co_u32_e32 v9, vcc, 0, v5, vcc
	global_load_dword v32, v[8:9], off
	global_load_dword v37, v7, s[66:67]
	v_add_co_u32_e32 v8, vcc, 0x320000, v4
	v_fmac_f32_e32 v66, v68, v71
	s_nop 0
	v_addc_co_u32_e32 v9, vcc, 0, v5, vcc
	global_load_dword v30, v[8:9], off
	global_load_dword v35, v7, s[68:69]
	v_add_co_u32_e32 v8, vcc, 0x330000, v4
	v_fmac_f32_e32 v64, v66, v69
	s_nop 0
	v_addc_co_u32_e32 v9, vcc, 0, v5, vcc
	global_load_dword v28, v[8:9], off
	global_load_dword v33, v7, s[4:5]
	v_add_co_u32_e32 v8, vcc, 0x340000, v4
	v_fmac_f32_e32 v62, v64, v67
	s_nop 0
	v_addc_co_u32_e32 v9, vcc, 0, v5, vcc
	global_load_dword v26, v[8:9], off
	global_load_dword v31, v7, s[10:11]
	v_add_co_u32_e32 v8, vcc, 0x350000, v4
	v_fmac_f32_e32 v60, v62, v65
	s_nop 0
	v_addc_co_u32_e32 v9, vcc, 0, v5, vcc
	global_load_dword v24, v[8:9], off
	global_load_dword v29, v7, s[12:13]
	v_add_co_u32_e32 v8, vcc, 0x360000, v4
	v_fmac_f32_e32 v58, v60, v63
	s_nop 0
	v_addc_co_u32_e32 v9, vcc, 0, v5, vcc
	global_load_dword v23, v[8:9], off
	global_load_dword v27, v7, s[14:15]
	v_add_co_u32_e32 v8, vcc, 0x370000, v4
	v_fmac_f32_e32 v56, v58, v61
	s_nop 0
	v_addc_co_u32_e32 v9, vcc, 0, v5, vcc
	global_load_dword v20, v[8:9], off
	global_load_dword v25, v7, s[16:17]
	v_add_co_u32_e32 v8, vcc, 0x380000, v4
	v_fmac_f32_e32 v54, v56, v59
	s_nop 0
	v_addc_co_u32_e32 v9, vcc, 0, v5, vcc
	global_load_dword v19, v[8:9], off
	global_load_dword v22, v7, s[18:19]
	v_add_co_u32_e32 v8, vcc, 0x390000, v4
	v_fmac_f32_e32 v52, v54, v57
	s_nop 0
	v_addc_co_u32_e32 v9, vcc, 0, v5, vcc
	global_load_dword v16, v[8:9], off
	global_load_dword v21, v7, s[20:21]
	v_add_co_u32_e32 v8, vcc, 0x3a0000, v4
	v_fmac_f32_e32 v50, v52, v55
	s_nop 0
	v_addc_co_u32_e32 v9, vcc, 0, v5, vcc
	global_load_dword v15, v[8:9], off
	global_load_dword v18, v7, s[22:23]
	v_add_co_u32_e32 v8, vcc, 0x3b0000, v4
	v_fmac_f32_e32 v48, v50, v53
	s_nop 0
	v_addc_co_u32_e32 v9, vcc, 0, v5, vcc
	global_load_dword v12, v[8:9], off
	global_load_dword v17, v7, s[24:25]
	v_add_co_u32_e32 v8, vcc, 0x3c0000, v4
	v_fmac_f32_e32 v46, v48, v51
	s_nop 0
	v_addc_co_u32_e32 v9, vcc, 0, v5, vcc
	global_load_dword v11, v[8:9], off
	global_load_dword v14, v7, s[26:27]
	v_add_co_u32_e32 v8, vcc, 0x3d0000, v4
	v_fmac_f32_e32 v44, v46, v49
	s_nop 0
	v_addc_co_u32_e32 v9, vcc, 0, v5, vcc
	v_add_co_u32_e32 v134, vcc, 0x3e0000, v4
	global_load_dword v9, v[8:9], off
	s_nop 0
	global_load_dword v13, v7, s[28:29]
	v_addc_co_u32_e32 v135, vcc, 0, v5, vcc
	v_add_co_u32_e32 v4, vcc, 0x3f0000, v4
	global_load_dword v8, v[134:135], off
	global_load_dword v10, v7, s[30:31]
	v_addc_co_u32_e32 v5, vcc, 0, v5, vcc
	v_add_co_u32_e32 v134, vcc, 0x8000, v2
	global_load_dword v4, v[4:5], off
	s_nop 0
	global_load_dword v5, v7, s[34:35]
	v_addc_co_u32_e32 v135, vcc, 0, v3, vcc
	v_add_co_u32_e32 v132, vcc, s43, v2
	global_store_short_d16_hi v[134:135], v133, off
	s_nop 0
	v_addc_co_u32_e32 v133, vcc, 0, v3, vcc
	global_store_short_d16_hi v[132:133], v130, off
	v_add_co_u32_e32 v130, vcc, 0x18000, v2
	s_mov_b32 s43, 0x20000
	s_nop 0
	v_addc_co_u32_e32 v131, vcc, 0, v3, vcc
	global_store_short_d16_hi v[130:131], v128, off
	v_add_co_u32_e32 v128, vcc, s43, v2
	s_mov_b32 s43, 0x30000
	s_nop 0
	v_addc_co_u32_e32 v129, vcc, 0, v3, vcc
	global_store_short_d16_hi v[128:129], v126, off
	v_add_co_u32_e32 v126, vcc, 0x28000, v2
	v_fmac_f32_e32 v42, v44, v47
	s_nop 0
	v_addc_co_u32_e32 v127, vcc, 0, v3, vcc
	global_store_short_d16_hi v[126:127], v124, off
	v_add_co_u32_e32 v124, vcc, s43, v2
	s_mov_b32 s43, 0x40000
	s_nop 0
	v_addc_co_u32_e32 v125, vcc, 0, v3, vcc
	global_store_short_d16_hi v[124:125], v122, off
	v_add_co_u32_e32 v122, vcc, 0x38000, v2
	s_waitcnt vmcnt(0)
	v_fmac_f32_e32 v40, v42, v45
	v_addc_co_u32_e32 v123, vcc, 0, v3, vcc
	global_store_short_d16_hi v[122:123], v120, off
	v_add_co_u32_e32 v120, vcc, s43, v2
	s_mov_b32 s43, 0x50000
	s_nop 0
	v_addc_co_u32_e32 v121, vcc, 0, v3, vcc
	global_store_short_d16_hi v[120:121], v118, off
	v_add_co_u32_e32 v118, vcc, 0x48000, v2
	v_fmac_f32_e32 v38, v40, v43
	s_nop 0
	v_addc_co_u32_e32 v119, vcc, 0, v3, vcc
	global_store_short_d16_hi v[118:119], v116, off
	v_add_co_u32_e32 v116, vcc, s43, v2
	s_mov_b32 s43, 0x60000
	s_nop 0
	v_addc_co_u32_e32 v117, vcc, 0, v3, vcc
	global_store_short_d16_hi v[116:117], v113, off
	v_add_co_u32_e32 v116, vcc, 0x58000, v2
	v_fmac_f32_e32 v36, v38, v41
	s_nop 0
	v_addc_co_u32_e32 v117, vcc, 0, v3, vcc
	v_add_co_u32_e32 v114, vcc, s43, v2
	s_mov_b32 s43, 0x70000
	s_nop 0
	v_addc_co_u32_e32 v115, vcc, 0, v3, vcc
	v_add_co_u32_e32 v112, vcc, 0x68000, v2
	global_store_short_d16_hi v[116:117], v111, off
	s_nop 0
	v_addc_co_u32_e32 v113, vcc, 0, v3, vcc
	v_add_co_u32_e32 v110, vcc, s43, v2
	global_store_short_d16_hi v[114:115], v109, off
	s_nop 0
	v_addc_co_u32_e32 v111, vcc, 0, v3, vcc
	v_add_co_u32_e32 v108, vcc, 0x78000, v2
	s_mov_b32 s43, 0x80000
	s_nop 0
	v_addc_co_u32_e32 v109, vcc, 0, v3, vcc
	v_add_co_u32_e32 v106, vcc, s43, v2
	global_store_short_d16_hi v[112:113], v107, off
	s_nop 0
	v_addc_co_u32_e32 v107, vcc, 0, v3, vcc
	v_add_co_u32_e32 v104, vcc, 0x88000, v2
	global_store_short_d16_hi v[110:111], v105, off
	s_nop 0
	v_addc_co_u32_e32 v105, vcc, 0, v3, vcc
	s_mov_b32 s43, 0x90000
	v_add_co_u32_e32 v102, vcc, s43, v2
	global_store_short_d16_hi v[108:109], v103, off
	s_nop 0
	v_addc_co_u32_e32 v103, vcc, 0, v3, vcc
	v_add_co_u32_e32 v100, vcc, 0x98000, v2
	global_store_short_d16_hi v[106:107], v101, off
	s_nop 0
	v_addc_co_u32_e32 v101, vcc, 0, v3, vcc
	s_mov_b32 s43, 0xa0000
	v_add_co_u32_e32 v98, vcc, s43, v2
	global_store_short_d16_hi v[104:105], v99, off
	s_nop 0
	v_addc_co_u32_e32 v99, vcc, 0, v3, vcc
	v_add_co_u32_e32 v96, vcc, 0xa8000, v2
	global_store_short_d16_hi v[102:103], v97, off
	s_nop 0
	v_addc_co_u32_e32 v97, vcc, 0, v3, vcc
	s_mov_b32 s43, 0xb0000
	v_add_co_u32_e32 v94, vcc, s43, v2
	global_store_short_d16_hi v[100:101], v95, off
	s_nop 0
	v_addc_co_u32_e32 v95, vcc, 0, v3, vcc
	global_store_short_d16_hi v[96:97], v91, off
	v_add3_u32 v91, v86, v88, s42
	v_add_co_u32_e32 v88, vcc, 0xb8000, v2
	global_store_short_d16_hi v[94:95], v89, off
	s_nop 0
	v_addc_co_u32_e32 v89, vcc, 0, v3, vcc
	s_mov_b32 s43, 0xc0000
	global_store_short_d16_hi v[88:89], v91, off
	v_bfe_u32 v86, v84, 16, 1
	v_add_co_u32_e32 v88, vcc, s43, v2
	v_add3_u32 v86, v84, v86, s42
	s_nop 0
	v_addc_co_u32_e32 v89, vcc, 0, v3, vcc
	global_store_short_d16_hi v[88:89], v86, off
	v_bfe_u32 v84, v82, 16, 1
	v_add_co_u32_e32 v86, vcc, 0xc8000, v2
	v_add3_u32 v84, v82, v84, s42
	s_nop 0
	v_addc_co_u32_e32 v87, vcc, 0, v3, vcc
	s_mov_b32 s43, 0xd0000
	global_store_short_d16_hi v[86:87], v84, off
	v_bfe_u32 v82, v80, 16, 1
	v_add_co_u32_e32 v84, vcc, s43, v2
	v_add3_u32 v82, v80, v82, s42
	s_nop 0
	v_addc_co_u32_e32 v85, vcc, 0, v3, vcc
	global_store_short_d16_hi v[84:85], v82, off
	v_bfe_u32 v80, v78, 16, 1
	v_add_co_u32_e32 v82, vcc, 0xd8000, v2
	v_add3_u32 v80, v78, v80, s42
	s_nop 0
	v_addc_co_u32_e32 v83, vcc, 0, v3, vcc
	s_mov_b32 s43, 0xe0000
	global_store_short_d16_hi v[82:83], v80, off
	v_bfe_u32 v78, v76, 16, 1
	v_add_co_u32_e32 v80, vcc, s43, v2
	v_add3_u32 v78, v76, v78, s42
	s_nop 0
	v_addc_co_u32_e32 v81, vcc, 0, v3, vcc
	global_store_short_d16_hi v[80:81], v78, off
	v_bfe_u32 v76, v74, 16, 1
	v_add_co_u32_e32 v78, vcc, 0xe8000, v2
	v_add3_u32 v76, v74, v76, s42
	s_nop 0
	v_addc_co_u32_e32 v79, vcc, 0, v3, vcc
	s_mov_b32 s43, 0xf0000
	global_store_short_d16_hi v[78:79], v76, off
	v_bfe_u32 v74, v72, 16, 1
	v_add_co_u32_e32 v76, vcc, s43, v2
	v_add3_u32 v74, v72, v74, s42
	s_nop 0
	v_addc_co_u32_e32 v77, vcc, 0, v3, vcc
	global_store_short_d16_hi v[76:77], v74, off
	v_bfe_u32 v72, v70, 16, 1
	v_add_co_u32_e32 v74, vcc, 0xf8000, v2
	v_add3_u32 v72, v70, v72, s42
	s_nop 0
	v_addc_co_u32_e32 v75, vcc, 0, v3, vcc
	s_mov_b32 s43, 0x100000
	global_store_short_d16_hi v[74:75], v72, off
	v_bfe_u32 v70, v68, 16, 1
	v_add_co_u32_e32 v72, vcc, s43, v2
	v_add3_u32 v70, v68, v70, s42
	s_nop 0
	v_addc_co_u32_e32 v73, vcc, 0, v3, vcc
	global_store_short_d16_hi v[72:73], v70, off
	v_bfe_u32 v68, v66, 16, 1
	v_add_co_u32_e32 v70, vcc, 0x108000, v2
	v_add3_u32 v68, v66, v68, s42
	s_nop 0
	v_addc_co_u32_e32 v71, vcc, 0, v3, vcc
	s_mov_b32 s43, 0x110000
	global_store_short_d16_hi v[70:71], v68, off
	v_bfe_u32 v66, v64, 16, 1
	v_add_co_u32_e32 v68, vcc, s43, v2
	v_add3_u32 v66, v64, v66, s42
	s_nop 0
	v_addc_co_u32_e32 v69, vcc, 0, v3, vcc
	global_store_short_d16_hi v[68:69], v66, off
	v_bfe_u32 v64, v62, 16, 1
	v_add_co_u32_e32 v66, vcc, 0x118000, v2
	v_add3_u32 v64, v62, v64, s42
	s_nop 0
	v_addc_co_u32_e32 v67, vcc, 0, v3, vcc
	s_mov_b32 s43, 0x120000
	global_store_short_d16_hi v[66:67], v64, off
	v_bfe_u32 v62, v60, 16, 1
	v_add_co_u32_e32 v64, vcc, s43, v2
	v_add3_u32 v62, v60, v62, s42
	s_nop 0
	v_addc_co_u32_e32 v65, vcc, 0, v3, vcc
	global_store_short_d16_hi v[64:65], v62, off
	v_bfe_u32 v60, v58, 16, 1
	v_add_co_u32_e32 v62, vcc, 0x128000, v2
	v_add3_u32 v60, v58, v60, s42
	s_nop 0
	v_addc_co_u32_e32 v63, vcc, 0, v3, vcc
	s_mov_b32 s43, 0x130000
	global_store_short_d16_hi v[62:63], v60, off
	v_bfe_u32 v58, v56, 16, 1
	v_add_co_u32_e32 v60, vcc, s43, v2
	v_add3_u32 v58, v56, v58, s42
	s_nop 0
	v_addc_co_u32_e32 v61, vcc, 0, v3, vcc
	global_store_short_d16_hi v[60:61], v58, off
	v_bfe_u32 v56, v54, 16, 1
	v_add_co_u32_e32 v58, vcc, 0x138000, v2
	v_add3_u32 v56, v54, v56, s42
	s_nop 0
	v_addc_co_u32_e32 v59, vcc, 0, v3, vcc
	s_mov_b32 s43, 0x140000
	global_store_short_d16_hi v[58:59], v56, off
	v_bfe_u32 v54, v52, 16, 1
	v_add_co_u32_e32 v56, vcc, s43, v2
	v_add3_u32 v54, v52, v54, s42
	s_nop 0
	v_addc_co_u32_e32 v57, vcc, 0, v3, vcc
	global_store_short_d16_hi v[56:57], v54, off
	v_bfe_u32 v52, v50, 16, 1
	v_add_co_u32_e32 v54, vcc, 0x148000, v2
	v_add3_u32 v52, v50, v52, s42
	s_nop 0
	v_addc_co_u32_e32 v55, vcc, 0, v3, vcc
	s_mov_b32 s43, 0x150000
	global_store_short_d16_hi v[54:55], v52, off
	v_bfe_u32 v50, v48, 16, 1
	v_add_co_u32_e32 v52, vcc, s43, v2
	v_add3_u32 v50, v48, v50, s42
	s_nop 0
	v_addc_co_u32_e32 v53, vcc, 0, v3, vcc
	global_store_short_d16_hi v[52:53], v50, off
	v_bfe_u32 v48, v46, 16, 1
	v_add_co_u32_e32 v50, vcc, 0x158000, v2
	v_add3_u32 v48, v46, v48, s42
	s_nop 0
	v_addc_co_u32_e32 v51, vcc, 0, v3, vcc
	s_mov_b32 s43, 0x160000
	global_store_short_d16_hi v[50:51], v48, off
	v_bfe_u32 v46, v44, 16, 1
	v_add_co_u32_e32 v48, vcc, s43, v2
	v_add3_u32 v46, v44, v46, s42
	s_nop 0
	v_addc_co_u32_e32 v49, vcc, 0, v3, vcc
	global_store_short_d16_hi v[48:49], v46, off
	v_bfe_u32 v44, v42, 16, 1
	v_add_co_u32_e32 v46, vcc, 0x168000, v2
	v_add3_u32 v44, v42, v44, s42
	s_nop 0
	v_addc_co_u32_e32 v47, vcc, 0, v3, vcc
	s_mov_b32 s43, 0x170000
	global_store_short_d16_hi v[46:47], v44, off
	v_bfe_u32 v42, v40, 16, 1
	v_add_co_u32_e32 v44, vcc, s43, v2
	v_add3_u32 v42, v40, v42, s42
	s_nop 0
	v_addc_co_u32_e32 v45, vcc, 0, v3, vcc
	global_store_short_d16_hi v[44:45], v42, off
	v_bfe_u32 v40, v38, 16, 1
	v_add_co_u32_e32 v42, vcc, 0x178000, v2
	v_add3_u32 v40, v38, v40, s42
	s_nop 0
	v_addc_co_u32_e32 v43, vcc, 0, v3, vcc
	s_mov_b32 s43, 0x180000
	global_store_short_d16_hi v[42:43], v40, off
	v_bfe_u32 v38, v36, 16, 1
	v_add_co_u32_e32 v40, vcc, s43, v2
	v_add3_u32 v38, v36, v38, s42
	s_nop 0
	v_addc_co_u32_e32 v41, vcc, 0, v3, vcc
	v_fmac_f32_e32 v34, v36, v39
	global_store_short_d16_hi v[40:41], v38, off
	v_bfe_u32 v36, v34, 16, 1
	v_add_co_u32_e32 v38, vcc, 0x188000, v2
	v_add3_u32 v36, v34, v36, s42
	s_nop 0
	v_addc_co_u32_e32 v39, vcc, 0, v3, vcc
	v_fmac_f32_e32 v32, v34, v37
	s_mov_b32 s43, 0x190000
	global_store_short_d16_hi v[38:39], v36, off
	v_bfe_u32 v34, v32, 16, 1
	v_add_co_u32_e32 v36, vcc, s43, v2
	v_add3_u32 v34, v32, v34, s42
	s_nop 0
	v_addc_co_u32_e32 v37, vcc, 0, v3, vcc
	v_fmac_f32_e32 v30, v32, v35
	global_store_short_d16_hi v[36:37], v34, off
	v_bfe_u32 v32, v30, 16, 1
	v_add_co_u32_e32 v34, vcc, 0x198000, v2
	v_add3_u32 v32, v30, v32, s42
	s_nop 0
	v_addc_co_u32_e32 v35, vcc, 0, v3, vcc
	v_fmac_f32_e32 v28, v30, v33
	s_mov_b32 s43, 0x1a0000
	global_store_short_d16_hi v[34:35], v32, off
	v_bfe_u32 v30, v28, 16, 1
	v_add_co_u32_e32 v32, vcc, s43, v2
	v_add3_u32 v30, v28, v30, s42
	s_nop 0
	v_addc_co_u32_e32 v33, vcc, 0, v3, vcc
	v_fmac_f32_e32 v26, v28, v31
	global_store_short_d16_hi v[32:33], v30, off
	v_bfe_u32 v28, v26, 16, 1
	v_add_co_u32_e32 v30, vcc, 0x1a8000, v2
	v_add3_u32 v28, v26, v28, s42
	s_nop 0
	v_addc_co_u32_e32 v31, vcc, 0, v3, vcc
	v_fmac_f32_e32 v24, v26, v29
	s_mov_b32 s43, 0x1b0000
	global_store_short_d16_hi v[30:31], v28, off
	v_bfe_u32 v26, v24, 16, 1
	v_add_co_u32_e32 v28, vcc, s43, v2
	v_add3_u32 v26, v24, v26, s42
	s_nop 0
	v_addc_co_u32_e32 v29, vcc, 0, v3, vcc
	v_fmac_f32_e32 v23, v24, v27
	global_store_short_d16_hi v[28:29], v26, off
	v_bfe_u32 v24, v23, 16, 1
	v_add_co_u32_e32 v26, vcc, 0x1b8000, v2
	v_add3_u32 v24, v23, v24, s42
	s_nop 0
	v_addc_co_u32_e32 v27, vcc, 0, v3, vcc
	s_mov_b32 s43, 0x1c0000
	global_store_short_d16_hi v[26:27], v24, off
	v_fmac_f32_e32 v20, v23, v25
	v_add_co_u32_e32 v24, vcc, s43, v2
	v_bfe_u32 v23, v20, 16, 1
	s_nop 0
	v_addc_co_u32_e32 v25, vcc, 0, v3, vcc
	v_fmac_f32_e32 v19, v20, v22
	v_add3_u32 v23, v20, v23, s42
	v_bfe_u32 v20, v19, 16, 1
	v_add_co_u32_e32 v22, vcc, 0x1c8000, v2
	global_store_short_d16_hi v[24:25], v23, off
	v_add3_u32 v20, v19, v20, s42
	v_addc_co_u32_e32 v23, vcc, 0, v3, vcc
	s_mov_b32 s43, 0x1d0000
	global_store_short_d16_hi v[22:23], v20, off
	v_fmac_f32_e32 v16, v19, v21
	v_add_co_u32_e32 v20, vcc, s43, v2
	v_bfe_u32 v19, v16, 16, 1
	s_nop 0
	v_addc_co_u32_e32 v21, vcc, 0, v3, vcc
	v_fmac_f32_e32 v15, v16, v18
	v_add3_u32 v19, v16, v19, s42
	v_bfe_u32 v16, v15, 16, 1
	v_add_co_u32_e32 v18, vcc, 0x1d8000, v2
	global_store_short_d16_hi v[20:21], v19, off
	v_add3_u32 v16, v15, v16, s42
	v_addc_co_u32_e32 v19, vcc, 0, v3, vcc
	s_mov_b32 s43, 0x1e0000
	global_store_short_d16_hi v[18:19], v16, off
	v_fmac_f32_e32 v12, v15, v17
	v_add_co_u32_e32 v16, vcc, s43, v2
	v_bfe_u32 v15, v12, 16, 1
	s_nop 0
	v_addc_co_u32_e32 v17, vcc, 0, v3, vcc
	v_fmac_f32_e32 v11, v12, v14
	v_add3_u32 v15, v12, v15, s42
	v_bfe_u32 v12, v11, 16, 1
	v_add_co_u32_e32 v14, vcc, 0x1e8000, v2
	global_store_short_d16_hi v[16:17], v15, off
	v_add3_u32 v12, v11, v12, s42
	v_addc_co_u32_e32 v15, vcc, 0, v3, vcc
	s_mov_b32 s43, 0x1f0000
	global_store_short_d16_hi v[14:15], v12, off
	v_add_co_u32_e32 v12, vcc, s43, v2
	v_fmac_f32_e32 v9, v11, v13
	s_nop 0
	v_addc_co_u32_e32 v13, vcc, 0, v3, vcc
	global_store_short v[2:3], v7, off
	v_bfe_u32 v11, v9, 16, 1
	v_fmac_f32_e32 v8, v9, v10
	v_add_co_u32_e32 v2, vcc, 0x1f8000, v2
	v_add3_u32 v11, v9, v11, s42
	v_bfe_u32 v9, v8, 16, 1
	v_addc_co_u32_e32 v3, vcc, 0, v3, vcc
	v_add3_u32 v9, v8, v9, s42
	v_fmac_f32_e32 v4, v8, v5
	s_mov_b32 s43, 64
	s_and_b64 vcc, exec, s[0:1]
	global_store_short_d16_hi v[98:99], v93, off
	global_store_short_d16_hi v[12:13], v11, off
	global_store_short_d16_hi v[2:3], v9, off
	global_store_dword v[0:1], v4, off
	s_cbranch_vccz .LBB0_1057
	s_mov_b32 s99, 64
	s_mov_b32 s100, 0
.Lcfin_items:
	v_readlane_b32 s0, v238, 3
	s_add_i32 s33, s0, s33
	s_lshr_b32 s0, s100, 5
	s_add_i32 s33, s33, s0
	v_readlane_b32 s96, v238, 5
	v_readlane_b32 s64, v239, 51
	v_readlane_b32 s80, v238, 36
	s_cmp_ge_i32 s33, s99
	v_readlane_b32 s92, v238, 38
	v_readlane_b32 s94, v238, 40
	v_readlane_b32 s87, v238, 4
	v_readlane_b32 s97, v238, 6
	v_readlane_b32 s84, v238, 7
	v_readlane_b32 s65, v239, 52
	v_readlane_b32 s68, v239, 55
	v_readlane_b32 s69, v239, 56
	v_readlane_b32 s76, v239, 63
	v_readlane_b32 s77, v238, 0
	v_readlane_b32 s81, v238, 37
	v_readlane_b32 s93, v238, 39
	v_readlane_b32 s95, v238, 41
	v_readlane_b32 s66, v239, 53
	v_readlane_b32 s67, v239, 54
	v_readlane_b32 s70, v239, 57
	v_readlane_b32 s71, v239, 58
	v_readlane_b32 s72, v239, 59
	v_readlane_b32 s73, v239, 60
	v_readlane_b32 s74, v239, 61
	v_readlane_b32 s75, v239, 62
	v_readlane_b32 s78, v238, 1
	v_readlane_b32 s79, v238, 2
	s_cbranch_scc1 .LBB0_1221
	v_lshrrev_b32_e32 v1, 5, v6
	v_lshlrev_b32_e32 v66, 2, v1
	v_lshlrev_b32_e32 v0, 3, v1
	v_lshlrev_b32_e32 v64, 4, v1
	v_add_u32_e32 v1, 24, v66
	v_and_b32_e32 v5, 64, v6
	v_lshrrev_b32_e32 v99, 5, v1
	v_and_b32_e32 v100, 28, v1
	v_add_u32_e32 v1, 40, v66
	v_xor_b32_e32 v3, 32, v6
	v_add_u32_e32 v5, 64, v5
	v_and_b32_e32 v101, 28, v1
	v_add_u32_e32 v1, 56, v66
	s_add_u32 s2, s90, 0x37971600
	v_mov_b32_e32 v65, 0
	v_cmp_lt_i32_e32 vcc, v3, v5
	v_lshrrev_b32_e32 v102, 5, v1
	v_and_b32_e32 v103, 28, v1
	v_add_u32_e32 v1, 0x48, v66
	s_addc_u32 s3, s91, 0
	v_and_b32_e32 v67, 31, v6
	v_cndmask_b32_e32 v3, v6, v3, vcc
	v_and_b32_e32 v104, 28, v1
	v_add_u32_e32 v1, 0x58, v66
	v_lshl_add_u64 v[6:7], s[90:91], 0, v[64:65]
	s_mov_b64 s[0:1], 0x52149600
	s_add_u32 s8, s90, 0x3b971600
	v_lshlrev_b32_e32 v2, 7, v67
	v_readlane_b32 s12, v239, 19
	v_lshrrev_b32_e32 v105, 5, v1
	v_and_b32_e32 v106, 28, v1
	v_add_u32_e32 v1, 0x68, v66
	v_lshl_add_u64 v[70:71], v[6:7], 0, s[0:1]
	v_readlane_b32 s1, v238, 3
	s_addc_u32 s9, s91, 0
	v_or_b32_e32 v4, 0x1000, v2
	v_or_b32_e32 v8, 0x2000, v2
	v_or_b32_e32 v10, 0x3000, v2
	v_readlane_b32 s13, v239, 20
	v_readlane_b32 s14, v239, 21
	v_readlane_b32 s15, v239, 22
	v_readlane_b32 s16, v239, 23
	v_readlane_b32 s17, v239, 24
	v_readlane_b32 s18, v239, 25
	v_readlane_b32 s19, v239, 26
	v_readlane_b32 s20, v239, 27
	v_readlane_b32 s21, v239, 28
	v_readlane_b32 s22, v239, 29
	v_readlane_b32 s23, v239, 30
	v_and_b32_e32 v107, 28, v1
	v_add_u32_e32 v1, 0x78, v66
	s_lshl_b32 s0, s94, 8
	s_lshl_b32 s1, s1, 5
	v_lshlrev_b32_e32 v96, 2, v3
	v_lshl_add_u64 v[68:69], s[16:17], 0, v[64:65]
	v_add_u32_e32 v97, 8, v66
	v_or_b32_e32 v98, 16, v66
	v_lshrrev_b32_e32 v108, 5, v1
	v_and_b32_e32 v109, 28, v1
	s_lshl_b32 s34, s92, 3
	s_add_i32 s35, s0, s1
	s_add_i32 s35, s35, s100
	s_lshl_b32 s36, s92, 8
	s_movk_i32 s37, 0x7f7
	s_movk_i32 s38, 0x1ff
	s_mov_b64 s[10:11], 0x400
	s_mov_b32 s39, 0x8000
	s_mov_b32 s40, 0x80808081
	s_movk_i32 s41, 0xff
	s_mov_b64 s[12:13], 0x800
	v_lshlrev_b32_e32 v72, 2, v0
	v_lshlrev_b32_e32 v74, 1, v2
	v_lshlrev_b32_e32 v76, 1, v4
	v_lshlrev_b32_e32 v78, 1, v8
	v_lshlrev_b32_e32 v80, 1, v10
	s_mov_b64 s[14:15], 0x60
	s_mov_b64 s[16:17], 0x80
	s_mov_b64 s[18:19], 0xa0
	s_mov_b64 s[20:21], 0xc0
	s_mov_b64 s[22:23], 0xe0
	v_mov_b32_e32 v110, 0x358637bd
	s_mov_b32 s42, 0x800000
	s_mov_b32 s43, 0x26cf1600
	s_movk_i32 s44, 0x7fff
	v_or3_b32 v83, 0, 0, 0
	v_mov_b32_e32 v111, 0x1232b600
	v_mov_b32_e32 v112, 0x1132b600
	v_readlane_b32 s24, v239, 31
	v_readlane_b32 s25, v239, 32
	v_readlane_b32 s26, v239, 33
	v_readlane_b32 s27, v239, 34
	s_branch .LBB0_1061
.LBB0_1060:
	s_or_b64 exec, exec, s[24:25]
	s_add_i32 s33, s33, s34
	s_add_i32 s35, s35, s36
	s_cmp_lt_i32 s33, s99
	s_cbranch_scc0 .LBB0_1220

.LBB0_1220:
	v_readlane_b32 s64, v239, 51
	v_readlane_b32 s65, v239, 52
	v_readlane_b32 s68, v239, 55
	v_readlane_b32 s69, v239, 56
	v_readlane_b32 s76, v239, 63
	v_readlane_b32 s77, v238, 0
	v_readlane_b32 s66, v239, 53
	v_readlane_b32 s67, v239, 54
	v_readlane_b32 s70, v239, 57
	v_readlane_b32 s71, v239, 58
	v_readlane_b32 s72, v239, 59
	v_readlane_b32 s73, v239, 60
	v_readlane_b32 s74, v239, 61
	v_readlane_b32 s75, v239, 62
	v_readlane_b32 s78, v238, 1
	v_readlane_b32 s79, v238, 2
	s_cmp_lg_u32 s99, 64
	s_cbranch_scc1 .Lcfin_ret

.LBB0_1308:
	v_readlane_b32 s101, v239, 35
	s_bitcmp1_b32 s94, 0
	s_cbranch_scc1 .Lattn_first
	s_cmpk_lt_i32 s94, 0x400
	s_cbranch_scc1 .LBB0_1310

.LBB0_1310:
	v_writelane_b32 v239, s101, 35
	s_movk_i32 s99, 0x840
	s_cmp_lt_u32 s94, 8
	s_cselect_b32 s100, 0x10000, 0
	s_lshl_b32 s33, s94, 3
	v_mbcnt_hi_u32_b32 v6, -1, v216
	s_branch .Lcfin_items
.Lcfin_ret:
	s_lshl_b32 s10, s94, 1
	s_lshr_b32 s62, s87, 8
